# GEMM loops: first iteration of each unit peeled with SrcC=0 on the first MFMA of every accumulator (accumulator zero-init removed); fragment reads stay directly in front of the first load segment
# speedup vs baseline: 1.0076x; 1.0076x over previous
.LBB0_445:
	s_add_u32 s56, s62, 0xb0080
	s_addc_u32 s57, s63, 0
	s_add_u32 s62, s60, 0x100
	v_mov_b32_e32 v2, 0
	s_addc_u32 s63, s61, 0
	s_mov_b32 s84, -2
	s_waitcnt lgkmcnt(0)
	s_add_i32 s22, 0, 0x10000
	s_add_i32 s23, 0, 0x14000
	v_add_u32_e32 v134, s22, v191
	v_add_u32_e32 v182, s23, v191
	ds_read_b128 v[114:117], v134
	ds_read_b128 v[126:129], v134 offset:1024
	ds_read_b128 v[130:133], v134 offset:2048
	ds_read_b128 v[134:137], v134 offset:3072
	ds_read_b128 v[146:149], v182
	ds_read_b128 v[150:153], v182 offset:1024
	ds_read_b128 v[158:161], v182 offset:2048
	ds_read_b128 v[182:185], v182 offset:3072
	ds_read_b128 v[186:189], v193
	ds_read_b128 v[194:197], v193 offset:1024
	ds_read_b128 v[198:201], v193 offset:2048
	ds_read_b128 v[214:217], v193 offset:3072
	ds_read_b128 v[218:221], v193 offset:4096
	ds_read_b128 v[222:225], v193 offset:5120
	ds_read_b128 v[226:229], v193 offset:6144
	ds_read_b128 v[230:233], v193 offset:7168
	s_mov_b64 s[12:13], 0xb0000
	s_mov_b64 s[86:87], 0x108000
	s_mov_b64 s[96:97], 0x58080
	s_mov_b64 vcc, 0xb0080
	s_mov_b64 s[0:1], 0x108080
	s_branch .Lmid1_446

.LBB0_487:
	s_ashr_i32 s57, s56, 31
	s_lshl_b64 s[20:21], s[56:57], 19
	s_add_u32 s60, s94, s20
	s_addc_u32 s61, s95, s21
	s_and_b64 s[20:21], s[54:55], exec
	s_cselect_b32 s57, s61, s69
	s_cselect_b32 s86, s60, s68
	s_ashr_i32 s51, s50, 31
	s_lshl_b64 s[20:21], s[50:51], 19
	s_add_u32 s62, s15, s20
	s_addc_u32 s63, s42, s21
	s_and_b64 s[20:21], s[54:55], exec
	s_cselect_b32 s51, s63, s77
	s_cselect_b32 s87, s62, s76
	s_add_u32 s68, s68, 0x40080
	s_addc_u32 s69, s69, 0
	s_add_u32 s91, s76, 0x100
	v_mov_b32_e32 v2, 0
	s_addc_u32 s96, s77, 0
	s_mov_b32 s97, -2
	s_add_i32 s22, 0, 0x10000
	v_add_u32_e32 v152, s22, v139
	s_add_i32 s23, 0, 0x14000
	ds_read_b128 v[134:137], v152
	ds_read_b128 v[144:147], v152 offset:1024
	ds_read_b128 v[148:151], v152 offset:2048
	ds_read_b128 v[152:155], v152 offset:3072
	v_add_u32_e32 v186, s23, v139
	ds_read_b128 v[156:159], v186
	ds_read_b128 v[160:163], v186 offset:1024
	ds_read_b128 v[182:185], v186 offset:2048
	ds_read_b128 v[186:189], v186 offset:3072
	ds_read_b128 v[190:193], v142
	ds_read_b128 v[194:197], v142 offset:1024
	ds_read_b128 v[198:201], v142 offset:2048
	ds_read_b128 v[214:217], v142 offset:3072
	ds_read_b128 v[218:221], v142 offset:4096
	ds_read_b128 v[222:225], v142 offset:5120
	ds_read_b128 v[226:229], v142 offset:6144
	ds_read_b128 v[230:233], v142 offset:7168
	s_branch .Lmid1_488

.LBB0_603:
	s_ashr_i32 s51, s50, 31
	s_lshl_b64 s[20:21], s[50:51], 18
	s_add_u32 s78, s0, s20
	s_addc_u32 s79, s1, s21
	s_and_b64 s[20:21], s[56:57], exec
	s_cselect_b32 s42, s79, s7
	s_cselect_b32 s43, s78, s6
	s_ashr_i32 s49, s48, 31
	s_lshl_b64 s[20:21], s[48:49], 18
	s_add_u32 s40, s76, s20
	s_addc_u32 s41, s77, s21
	s_and_b64 s[20:21], s[56:57], exec
	s_cselect_b32 s46, s41, s69
	s_cselect_b32 s47, s40, s68
	s_add_u32 s6, s6, 0x20080
	s_addc_u32 s7, s7, 0
	s_add_u32 s49, s68, 0x100
	v_mov_b32_e32 v2, 0
	s_addc_u32 s51, s69, 0
	s_mov_b32 s84, -2
	s_waitcnt lgkmcnt(0)
	s_add_i32 s22, 0, 0x10000
	s_add_i32 s23, 0, 0x14000
	v_add_u32_e32 v150, s22, v139
	v_add_u32_e32 v186, s23, v139
	ds_read_b128 v[134:137], v150
	ds_read_b128 v[142:145], v150 offset:1024
	ds_read_b128 v[146:149], v150 offset:2048
	ds_read_b128 v[150:153], v150 offset:3072
	ds_read_b128 v[154:157], v186
	ds_read_b128 v[158:161], v186 offset:1024
	ds_read_b128 v[182:185], v186 offset:2048
	ds_read_b128 v[186:189], v186 offset:3072
	ds_read_b128 v[190:193], v141
	ds_read_b128 v[194:197], v141 offset:1024
	ds_read_b128 v[198:201], v141 offset:2048
	ds_read_b128 v[214:217], v141 offset:3072
	ds_read_b128 v[218:221], v141 offset:4096
	ds_read_b128 v[222:225], v141 offset:5120
	ds_read_b128 v[226:229], v141 offset:6144
	ds_read_b128 v[230:233], v141 offset:7168
	s_branch .Lmid1_604

.LBB0_777:
	s_ashr_i32 s61, s60, 31
	s_lshl_b64 s[20:21], s[60:61], 19
	s_add_u32 s62, s94, s20
	s_addc_u32 s63, s95, s21
	s_and_b64 s[20:21], s[56:57], exec
	s_cselect_b32 s61, s63, s77
	s_cselect_b32 s85, s62, s76
	s_ashr_i32 s59, s58, 31
	s_lshl_b64 s[20:21], s[58:59], 19
	s_add_u32 s68, s15, s20
	s_addc_u32 s69, s42, s21
	s_and_b64 s[20:21], s[56:57], exec
	s_cselect_b32 s59, s69, s79
	s_cselect_b32 s86, s68, s78
	s_add_u32 s76, s76, 0x40080
	s_addc_u32 s77, s77, 0
	s_add_u32 s87, s78, 0x100
	v_mov_b32_e32 v2, 0
	s_addc_u32 vcc_lo, s79, 0
	s_mov_b32 vcc_hi, -2
	s_waitcnt lgkmcnt(0)
	s_add_i32 s22, 0, 0x10000
	s_add_i32 s23, 0, 0x14000
	v_add_u32_e32 v142, s22, v193
	v_add_u32_e32 v158, s23, v193
	ds_read_b128 v[130:133], v142
	ds_read_b128 v[134:137], v142 offset:1024
	ds_read_b128 v[138:141], v142 offset:2048
	ds_read_b128 v[142:145], v142 offset:3072
	ds_read_b128 v[146:149], v158
	ds_read_b128 v[150:153], v158 offset:1024
	ds_read_b128 v[154:157], v158 offset:2048
	ds_read_b128 v[158:161], v158 offset:3072
	ds_read_b128 v[184:187], v196
	ds_read_b128 v[188:191], v196 offset:1024
	ds_read_b128 v[198:201], v196 offset:2048
	ds_read_b128 v[214:217], v196 offset:3072
	ds_read_b128 v[218:221], v196 offset:4096
	ds_read_b128 v[222:225], v196 offset:5120
	ds_read_b128 v[226:229], v196 offset:6144
	ds_read_b128 v[230:233], v196 offset:7168
	s_branch .Lmid1_778

.LBB0_849:
	s_ashr_i32 s79, s78, 31
	s_lshl_b64 s[20:21], s[78:79], 19
	s_add_u32 s88, s4, s20
	s_addc_u32 s89, s5, s21
	s_and_b64 s[20:21], s[54:55], exec
	s_cselect_b32 s76, s89, s57
	s_cselect_b32 s77, s88, s56
	s_ashr_i32 s69, s68, 31
	s_lshl_b64 s[20:21], s[68:69], 19
	v_readlane_b32 s12, v247, 42
	s_add_u32 s94, s12, s20
	v_readlane_b32 s12, v245, 61
	s_addc_u32 s95, s12, s21
	s_and_b64 s[20:21], s[54:55], exec
	s_cselect_b32 s69, s95, s59
	s_cselect_b32 s79, s94, s58
	s_add_u32 s56, s56, 0x40080
	s_addc_u32 s57, s57, 0
	s_add_u32 s86, s58, 0x100
	v_mov_b32_e32 v2, 0
	s_addc_u32 s87, s59, 0
	s_mov_b32 s91, -2
	s_add_i32 vcc_lo, 0, 0x10000
	v_add_u32_e32 v158, vcc_lo, v145
	s_add_i32 vcc_hi, 0, 0x14000
	ds_read_b128 v[138:141], v158
	ds_read_b128 v[146:149], v158 offset:1024
	ds_read_b128 v[150:153], v158 offset:2048
	ds_read_b128 v[158:161], v158 offset:3072
	v_add_u32_e32 v194, vcc_hi, v145
	ds_read_b128 v[182:185], v194
	ds_read_b128 v[186:189], v194 offset:1024
	ds_read_b128 v[190:193], v194 offset:2048
	ds_read_b128 v[194:197], v194 offset:3072
	ds_read_b128 v[198:201], v157
	ds_read_b128 v[214:217], v157 offset:1024
	ds_read_b128 v[218:221], v157 offset:2048
	ds_read_b128 v[222:225], v157 offset:3072
	ds_read_b128 v[226:229], v157 offset:4096
	ds_read_b128 v[230:233], v157 offset:5120
	ds_read_b128 v[234:237], v157 offset:6144
	ds_read_b128 v[238:241], v157 offset:7168
	s_branch .Lmid1_850
